# first workgroup arriving on an XCC starts the L2 write-back early (async), on top of the batched-load edits
# baseline (speedup 1.0000x reference)
.LBB0_98:
	s_or_b64 exec, exec, s[12:13]
	v_cvt_f32_u32_e32 v4, v2
	s_waitcnt vmcnt(0)
	v_readfirstlane_b32 s3, v3
	v_sub_u32_e32 v3, 0, v2
	v_rcp_iflag_f32_e32 v4, v4
	v_add_u32_e32 v5, s3, v1
	v_mul_f32_e32 v4, 0x4f7ffffe, v4
	v_cvt_u32_f32_e32 v4, v4
	v_mul_lo_u32 v1, v3, v4
	v_mul_hi_u32 v1, v4, v1
	v_add_u32_e32 v1, v4, v1
	v_mul_hi_u32 v1, v5, v1
	v_mul_lo_u32 v3, v1, v2
	v_sub_u32_e32 v3, v5, v3
	v_add_u32_e32 v4, 1, v1
	v_cmp_ge_u32_e32 vcc, v3, v2
	s_nop 1
	v_cndmask_b32_e32 v1, v1, v4, vcc
	v_sub_u32_e32 v4, v3, v2
	v_cndmask_b32_e32 v3, v3, v4, vcc
	v_add_u32_e32 v4, 1, v1
	v_cmp_ge_u32_e32 vcc, v3, v2
	v_add_u32_e32 v3, 1, v5
	s_nop 0
	v_cndmask_b32_e32 v1, v1, v4, vcc
	v_mul_lo_u32 v4, v2, v1
	v_add_u32_e32 v2, v4, v2
	v_cmp_ne_u32_e32 vcc, v3, v2
	s_and_saveexec_b64 s[10:11], vcc
	s_xor_b64 s[10:11], exec, s[10:11]
	s_cbranch_execz .LBB0_112
	v_cmp_eq_u32_e32 vcc, v5, v4
	s_cbranch_vccz .Lnofirst_0
	buffer_wbl2 sc1
.Lnofirst_0:
	s_waitcnt lgkmcnt(0)
	v_mov_b32_e32 v0, 0x2000
	global_load_dword v0, v0, s[8:9] offset:1024 sc1
	s_add_u32 s16, s8, 0x2400
	s_addc_u32 s17, s9, 0
	s_waitcnt vmcnt(0)
	v_cmp_eq_u32_e32 vcc, v0, v1
	s_and_saveexec_b64 s[12:13], vcc
	s_cbranch_execz .LBB0_111
	s_add_u32 s14, s66, 0x1dfd8200
	s_addc_u32 s15, s67, 0
	s_mov_b32 s3, 1
	s_mov_b64 s[18:19], 0
	v_mov_b32_e32 v0, 0
	s_branch .LBB0_102

.LBB0_160:
	s_or_b64 exec, exec, s[10:11]
	v_cvt_f32_u32_e32 v4, v2
	s_waitcnt vmcnt(0)
	v_readfirstlane_b32 s3, v3
	v_sub_u32_e32 v3, 0, v2
	v_rcp_iflag_f32_e32 v4, v4
	v_add_u32_e32 v5, s3, v1
	v_mul_f32_e32 v4, 0x4f7ffffe, v4
	v_cvt_u32_f32_e32 v4, v4
	v_mul_lo_u32 v1, v3, v4
	v_mul_hi_u32 v1, v4, v1
	v_add_u32_e32 v1, v4, v1
	v_mul_hi_u32 v1, v5, v1
	v_mul_lo_u32 v3, v1, v2
	v_sub_u32_e32 v3, v5, v3
	v_add_u32_e32 v4, 1, v1
	v_cmp_ge_u32_e32 vcc, v3, v2
	s_nop 1
	v_cndmask_b32_e32 v1, v1, v4, vcc
	v_sub_u32_e32 v4, v3, v2
	v_cndmask_b32_e32 v3, v3, v4, vcc
	v_add_u32_e32 v4, 1, v1
	v_cmp_ge_u32_e32 vcc, v3, v2
	v_add_u32_e32 v3, 1, v5
	s_nop 0
	v_cndmask_b32_e32 v1, v1, v4, vcc
	v_mul_lo_u32 v4, v2, v1
	v_add_u32_e32 v2, v4, v2
	v_cmp_ne_u32_e32 vcc, v3, v2
	s_and_saveexec_b64 s[8:9], vcc
	s_xor_b64 s[8:9], exec, s[8:9]
	s_cbranch_execz .LBB0_174
	v_cmp_eq_u32_e32 vcc, v5, v4
	s_cbranch_vccz .Lnofirst_1
	buffer_wbl2 sc1
.Lnofirst_1:
	s_waitcnt lgkmcnt(0)
	v_mov_b32_e32 v0, 0x2000
	global_load_dword v0, v0, s[6:7] offset:1024 sc1
	s_add_u32 s14, s6, 0x2400
	s_addc_u32 s15, s7, 0
	s_waitcnt vmcnt(0)
	v_cmp_eq_u32_e32 vcc, v0, v1
	s_and_saveexec_b64 s[10:11], vcc
	s_cbranch_execz .LBB0_173
	s_add_u32 s12, s66, 0x1dfd8200
	s_addc_u32 s13, s67, 0
	s_mov_b32 s3, 1
	s_mov_b64 s[16:17], 0
	v_mov_b32_e32 v0, 0
	s_branch .LBB0_164

.LBB0_266:
	s_or_b64 exec, exec, s[24:25]
	v_cvt_f32_u32_e32 v5, v3
	s_waitcnt vmcnt(0)
	v_readfirstlane_b32 s23, v4
	v_sub_u32_e32 v4, 0, v3
	v_rcp_iflag_f32_e32 v5, v5
	v_add_u32_e32 v6, s23, v0
	v_mul_f32_e32 v5, 0x4f7ffffe, v5
	v_cvt_u32_f32_e32 v5, v5
	v_mul_lo_u32 v0, v4, v5
	v_mul_hi_u32 v0, v5, v0
	v_add_u32_e32 v0, v5, v0
	v_mul_hi_u32 v0, v6, v0
	v_mul_lo_u32 v4, v0, v3
	v_sub_u32_e32 v4, v6, v4
	v_add_u32_e32 v5, 1, v0
	v_cmp_ge_u32_e32 vcc, v4, v3
	s_nop 1
	v_cndmask_b32_e32 v0, v0, v5, vcc
	v_sub_u32_e32 v5, v4, v3
	v_cndmask_b32_e32 v4, v4, v5, vcc
	v_add_u32_e32 v5, 1, v0
	v_cmp_ge_u32_e32 vcc, v4, v3
	v_add_u32_e32 v4, 1, v6
	s_nop 0
	v_cndmask_b32_e32 v0, v0, v5, vcc
	v_mul_lo_u32 v5, v3, v0
	v_add_u32_e32 v3, v5, v3
	v_cmp_ne_u32_e32 vcc, v4, v3
	s_and_saveexec_b64 s[24:25], vcc
	s_xor_b64 s[24:25], exec, s[24:25]
	s_cbranch_execz .LBB0_280
	v_cmp_eq_u32_e32 vcc, v6, v5
	s_cbranch_vccz .Lnofirst_2
	buffer_wbl2 sc1
.Lnofirst_2:
	v_readlane_b32 s28, v253, 48
	v_readlane_b32 s29, v253, 49
	s_waitcnt lgkmcnt(0)
	s_nop 3
	global_load_dword v2, v1, s[28:29] sc1
	s_waitcnt vmcnt(0)
	v_cmp_eq_u32_e32 vcc, v2, v0
	s_and_saveexec_b64 s[28:29], vcc
	s_cbranch_execz .LBB0_279
	s_mov_b32 s23, 1
	s_mov_b64 s[30:31], 0
	s_branch .LBB0_270

.LBB0_447:
	s_or_b64 exec, exec, s[24:25]
	v_cvt_f32_u32_e32 v5, v3
	s_waitcnt vmcnt(0)
	v_readfirstlane_b32 s22, v4
	v_sub_u32_e32 v4, 0, v3
	v_rcp_iflag_f32_e32 v5, v5
	v_add_u32_e32 v6, s22, v0
	v_mul_f32_e32 v5, 0x4f7ffffe, v5
	v_cvt_u32_f32_e32 v5, v5
	v_mul_lo_u32 v0, v4, v5
	v_mul_hi_u32 v0, v5, v0
	v_add_u32_e32 v0, v5, v0
	v_mul_hi_u32 v0, v6, v0
	v_mul_lo_u32 v4, v0, v3
	v_sub_u32_e32 v4, v6, v4
	v_add_u32_e32 v5, 1, v0
	v_cmp_ge_u32_e32 vcc, v4, v3
	s_nop 1
	v_cndmask_b32_e32 v0, v0, v5, vcc
	v_sub_u32_e32 v5, v4, v3
	v_cndmask_b32_e32 v4, v4, v5, vcc
	v_add_u32_e32 v5, 1, v0
	v_cmp_ge_u32_e32 vcc, v4, v3
	v_add_u32_e32 v4, 1, v6
	s_nop 0
	v_cndmask_b32_e32 v0, v0, v5, vcc
	v_mul_lo_u32 v5, v3, v0
	v_add_u32_e32 v3, v5, v3
	v_cmp_ne_u32_e32 vcc, v4, v3
	s_and_saveexec_b64 s[24:25], vcc
	s_xor_b64 s[24:25], exec, s[24:25]
	s_cbranch_execz .LBB0_461
	v_cmp_eq_u32_e32 vcc, v6, v5
	s_cbranch_vccz .Lnofirst_3
	buffer_wbl2 sc1
.Lnofirst_3:
	v_readlane_b32 s28, v253, 48
	v_readlane_b32 s29, v253, 49
	s_waitcnt lgkmcnt(0)
	s_nop 3
	global_load_dword v2, v1, s[28:29] sc1
	s_waitcnt vmcnt(0)
	v_cmp_eq_u32_e32 vcc, v2, v0
	s_and_saveexec_b64 s[28:29], vcc
	s_cbranch_execz .LBB0_460
	s_mov_b32 s22, 1
	s_mov_b64 s[30:31], 0
	s_branch .LBB0_451

.LBB0_528:
	s_or_b64 exec, exec, s[28:29]
	v_cvt_f32_u32_e32 v5, v3
	s_waitcnt vmcnt(0)
	v_readfirstlane_b32 s19, v4
	v_sub_u32_e32 v4, 0, v3
	v_rcp_iflag_f32_e32 v5, v5
	v_add_u32_e32 v6, s19, v0
	v_mul_f32_e32 v5, 0x4f7ffffe, v5
	v_cvt_u32_f32_e32 v5, v5
	v_mul_lo_u32 v0, v4, v5
	v_mul_hi_u32 v0, v5, v0
	v_add_u32_e32 v0, v5, v0
	v_mul_hi_u32 v0, v6, v0
	v_mul_lo_u32 v4, v0, v3
	v_sub_u32_e32 v4, v6, v4
	v_add_u32_e32 v5, 1, v0
	v_cmp_ge_u32_e32 vcc, v4, v3
	s_nop 1
	v_cndmask_b32_e32 v0, v0, v5, vcc
	v_sub_u32_e32 v5, v4, v3
	v_cndmask_b32_e32 v4, v4, v5, vcc
	v_add_u32_e32 v5, 1, v0
	v_cmp_ge_u32_e32 vcc, v4, v3
	v_add_u32_e32 v4, 1, v6
	s_nop 0
	v_cndmask_b32_e32 v0, v0, v5, vcc
	v_mul_lo_u32 v5, v3, v0
	v_add_u32_e32 v3, v5, v3
	v_cmp_ne_u32_e32 vcc, v4, v3
	s_and_saveexec_b64 s[22:23], vcc
	s_xor_b64 s[28:29], exec, s[22:23]
	s_cbranch_execz .LBB0_542
	v_cmp_eq_u32_e32 vcc, v6, v5
	s_cbranch_vccz .Lnofirst_4
	buffer_wbl2 sc1
.Lnofirst_4:
	v_readlane_b32 s22, v253, 48
	v_readlane_b32 s23, v253, 49
	s_waitcnt lgkmcnt(0)
	s_nop 3
	global_load_dword v2, v1, s[22:23] sc1
	s_waitcnt vmcnt(0)
	v_cmp_eq_u32_e32 vcc, v2, v0
	s_and_saveexec_b64 s[30:31], vcc
	s_cbranch_execz .LBB0_541
	s_mov_b32 s19, 1
	s_mov_b64 s[36:37], 0
	s_branch .LBB0_532

.LBB0_787:
	s_or_b64 exec, exec, s[18:19]
	v_cvt_f32_u32_e32 v5, v3
	s_waitcnt vmcnt(0)
	v_readfirstlane_b32 s18, v4
	v_sub_u32_e32 v4, 0, v3
	v_rcp_iflag_f32_e32 v5, v5
	v_add_u32_e32 v6, s18, v0
	v_mul_f32_e32 v5, 0x4f7ffffe, v5
	v_cvt_u32_f32_e32 v5, v5
	v_mul_lo_u32 v0, v4, v5
	v_mul_hi_u32 v0, v5, v0
	v_add_u32_e32 v0, v5, v0
	v_mul_hi_u32 v0, v6, v0
	v_mul_lo_u32 v4, v0, v3
	v_sub_u32_e32 v4, v6, v4
	v_add_u32_e32 v5, 1, v0
	v_cmp_ge_u32_e32 vcc, v4, v3
	s_nop 1
	v_cndmask_b32_e32 v0, v0, v5, vcc
	v_sub_u32_e32 v5, v4, v3
	v_cndmask_b32_e32 v4, v4, v5, vcc
	v_add_u32_e32 v5, 1, v0
	v_cmp_ge_u32_e32 vcc, v4, v3
	v_add_u32_e32 v4, 1, v6
	s_nop 0
	v_cndmask_b32_e32 v0, v0, v5, vcc
	v_mul_lo_u32 v5, v3, v0
	v_add_u32_e32 v3, v5, v3
	v_cmp_ne_u32_e32 vcc, v4, v3
	s_and_saveexec_b64 s[18:19], vcc
	s_xor_b64 s[18:19], exec, s[18:19]
	s_cbranch_execz .LBB0_801
	v_cmp_eq_u32_e32 vcc, v6, v5
	s_cbranch_vccz .Lnofirst_5
	buffer_wbl2 sc1
.Lnofirst_5:
	v_readlane_b32 s24, v253, 48
	v_readlane_b32 s25, v253, 49
	s_waitcnt lgkmcnt(0)
	s_nop 3
	global_load_dword v2, v1, s[24:25] sc1
	s_waitcnt vmcnt(0)
	v_cmp_eq_u32_e32 vcc, v2, v0
	s_and_saveexec_b64 s[24:25], vcc
	s_cbranch_execz .LBB0_800
	s_mov_b32 s22, 1
	s_mov_b64 s[28:29], 0
	s_branch .LBB0_791

.LBB0_871:
	s_or_b64 exec, exec, s[24:25]
	v_cvt_f32_u32_e32 v5, v3
	s_waitcnt vmcnt(0)
	v_readfirstlane_b32 s24, v4
	v_sub_u32_e32 v4, 0, v3
	v_rcp_iflag_f32_e32 v5, v5
	v_add_u32_e32 v6, s24, v0
	v_mul_f32_e32 v5, 0x4f7ffffe, v5
	v_cvt_u32_f32_e32 v5, v5
	v_mul_lo_u32 v0, v4, v5
	v_mul_hi_u32 v0, v5, v0
	v_add_u32_e32 v0, v5, v0
	v_mul_hi_u32 v0, v6, v0
	v_mul_lo_u32 v4, v0, v3
	v_sub_u32_e32 v4, v6, v4
	v_add_u32_e32 v5, 1, v0
	v_cmp_ge_u32_e32 vcc, v4, v3
	s_nop 1
	v_cndmask_b32_e32 v0, v0, v5, vcc
	v_sub_u32_e32 v5, v4, v3
	v_cndmask_b32_e32 v4, v4, v5, vcc
	v_add_u32_e32 v5, 1, v0
	v_cmp_ge_u32_e32 vcc, v4, v3
	v_add_u32_e32 v4, 1, v6
	s_nop 0
	v_cndmask_b32_e32 v0, v0, v5, vcc
	v_mul_lo_u32 v5, v3, v0
	v_add_u32_e32 v3, v5, v3
	v_cmp_ne_u32_e32 vcc, v4, v3
	s_and_saveexec_b64 s[24:25], vcc
	s_xor_b64 s[24:25], exec, s[24:25]
	s_cbranch_execz .LBB0_885
	v_cmp_eq_u32_e32 vcc, v6, v5
	s_cbranch_vccz .Lnofirst_6
	buffer_wbl2 sc1
.Lnofirst_6:
	v_readlane_b32 s28, v253, 48
	v_readlane_b32 s29, v253, 49
	s_waitcnt lgkmcnt(0)
	s_nop 3
	global_load_dword v2, v1, s[28:29] sc1
	s_waitcnt vmcnt(0)
	v_cmp_eq_u32_e32 vcc, v2, v0
	s_and_saveexec_b64 s[28:29], vcc
	s_cbranch_execz .LBB0_884
	s_mov_b32 s46, 1
	s_mov_b64 s[30:31], 0
	s_branch .LBB0_875
